# residual/norm GEMM epilogues (wo, w2): one burst of dword loads touches the whole residual tile before the serialized load-fma-store chain (L2 hits instead of 16 memory latencies)
# speedup vs baseline: 1.0013x; 1.0013x over previous
.LBB0_1323:
	s_ashr_i32 s10, s83, 31
	s_lshr_b32 s10, s10, 28
	s_add_i32 s10, s83, s10
	s_lshr_b32 s10, s10, 4
	s_mul_i32 s56, s10, 0x3000
	s_mov_b32 s57, s15
	v_lshl_add_u64 v[138:139], s[56:57], 2, v[206:207]
	global_load_dwordx4 v[142:145], v[138:139], off offset:16
	global_load_dwordx4 v[146:149], v[138:139], off
	global_load_dwordx4 v[134:137], v[138:139], off offset:528
	s_nop 0
	global_load_dwordx4 v[138:141], v[138:139], off offset:512
	s_lshl_b32 s14, s83, 19
	v_readlane_b32 s58, v255, 21
	s_lshl_b64 s[10:11], s[14:15], s79
	v_readlane_b32 s59, v255, 22
	v_lshl_add_u64 v[162:163], v[222:223], 0, s[10:11]
	v_mov_b32_e32 v246, v162
	v_mov_b32_e32 v247, v163
	s_cmp_eq_u32 s79, 2
	s_cbranch_scc0 .Lpf1_bf
	v_lshl_add_u64 v[246:247], v[246:247], 0, v[210:211]
.Lpf1_bf:
	s_movk_i32 s10, 0x80
	s_lshl_b32 s10, s10, s79
	s_mov_b32 s11, 0
	v_lshl_add_u64 v[248:249], v[246:247], 0, s[10:11]
	s_lshl_b32 s10, s10, 8
	global_load_dword v245, v[246:247], off
	global_load_dword v245, v[248:249], off
	v_lshl_add_u64 v[246:247], v[246:247], 0, s[10:11]
	v_lshl_add_u64 v[248:249], v[248:249], 0, s[10:11]
	global_load_dword v245, v[246:247], off
	global_load_dword v245, v[248:249], off
	v_lshl_add_u64 v[246:247], v[246:247], 0, s[10:11]
	v_lshl_add_u64 v[248:249], v[248:249], 0, s[10:11]
	global_load_dword v245, v[246:247], off
	global_load_dword v245, v[248:249], off
	v_lshl_add_u64 v[246:247], v[246:247], 0, s[10:11]
	v_lshl_add_u64 v[248:249], v[248:249], 0, s[10:11]
	global_load_dword v245, v[246:247], off
	global_load_dword v245, v[248:249], off
	v_lshl_add_u64 v[246:247], s[10:11], 2, v[246:247]
	v_lshl_add_u64 v[246:247], v[246:247], 0, s[10:11]
	v_lshl_add_u64 v[248:249], s[10:11], 2, v[248:249]
	v_lshl_add_u64 v[248:249], v[248:249], 0, s[10:11]
	global_load_dword v245, v[246:247], off
	global_load_dword v245, v[248:249], off
	v_lshl_add_u64 v[246:247], v[246:247], 0, s[10:11]
	v_lshl_add_u64 v[248:249], v[248:249], 0, s[10:11]
	global_load_dword v245, v[246:247], off
	global_load_dword v245, v[248:249], off
	v_lshl_add_u64 v[246:247], v[246:247], 0, s[10:11]
	v_lshl_add_u64 v[248:249], v[248:249], 0, s[10:11]
	global_load_dword v245, v[246:247], off
	global_load_dword v245, v[248:249], off
	v_lshl_add_u64 v[246:247], v[246:247], 0, s[10:11]
	v_lshl_add_u64 v[248:249], v[248:249], 0, s[10:11]
	global_load_dword v245, v[246:247], off
	global_load_dword v245, v[248:249], off
	s_mov_b64 s[10:11], -1
	s_and_b64 vcc, exec, s[58:59]
	s_cbranch_vccz .LBB0_1325
	global_load_dwordx4 v[150:153], v[162:163], off
	s_mov_b64 s[10:11], 0
	s_waitcnt vmcnt(0)
	v_lshlrev_b32_e32 v154, 16, v150
	v_and_b32_e32 v155, 0xffff0000, v150
	v_lshlrev_b32_e32 v156, 16, v151
	v_and_b32_e32 v157, 0xffff0000, v151
	v_lshlrev_b32_e32 v150, 16, v152
	v_and_b32_e32 v151, 0xffff0000, v152
	v_lshlrev_b32_e32 v152, 16, v153
	v_and_b32_e32 v153, 0xffff0000, v153

.LBB0_1645:
	s_ashr_i32 s0, s1, 31
	s_lshr_b32 s0, s0, 28
	s_add_i32 s0, s1, s0
	s_ashr_i32 s0, s0, 4
	s_mul_i32 s64, s0, 0x3000
	s_mov_b32 s65, s15
	s_lshl_b32 s14, s1, 19
	v_lshl_add_u64 v[138:139], s[64:65], 2, v[206:207]
	v_lshl_add_u64 v[150:151], s[14:15], 1, v[210:211]
	global_load_dwordx4 v[142:145], v[138:139], off offset:16
	global_load_dwordx4 v[146:149], v[138:139], off
	global_load_dwordx4 v[134:137], v[138:139], off offset:528
	s_nop 0
	global_load_dwordx4 v[138:141], v[138:139], off offset:512
	s_mov_b32 s2, 0x10000
	v_mov_b32_e32 v156, v150
	v_mov_b32_e32 v157, v151
	global_load_dword v158, v[156:157], off
	global_load_dword v158, v[156:157], off offset:256
	v_add_co_u32_e32 v156, vcc, s2, v156
	v_addc_co_u32_e32 v157, vcc, 0, v157, vcc
	global_load_dword v158, v[156:157], off
	global_load_dword v158, v[156:157], off offset:256
	v_add_co_u32_e32 v156, vcc, s2, v156
	v_addc_co_u32_e32 v157, vcc, 0, v157, vcc
	global_load_dword v158, v[156:157], off
	global_load_dword v158, v[156:157], off offset:256
	v_add_co_u32_e32 v156, vcc, s2, v156
	v_addc_co_u32_e32 v157, vcc, 0, v157, vcc
	global_load_dword v158, v[156:157], off
	global_load_dword v158, v[156:157], off offset:256
	v_add_co_u32_e32 v156, vcc, 0x50000, v156
	v_addc_co_u32_e32 v157, vcc, 0, v157, vcc
	global_load_dword v158, v[156:157], off
	global_load_dword v158, v[156:157], off offset:256
	v_add_co_u32_e32 v156, vcc, s2, v156
	v_addc_co_u32_e32 v157, vcc, 0, v157, vcc
	global_load_dword v158, v[156:157], off
	global_load_dword v158, v[156:157], off offset:256
	v_add_co_u32_e32 v156, vcc, s2, v156
	v_addc_co_u32_e32 v157, vcc, 0, v157, vcc
	global_load_dword v158, v[156:157], off
	global_load_dword v158, v[156:157], off offset:256
	v_add_co_u32_e32 v156, vcc, s2, v156
	v_addc_co_u32_e32 v157, vcc, 0, v157, vcc
	global_load_dword v158, v[156:157], off
	global_load_dword v158, v[156:157], off offset:256
	global_load_dwordx4 v[152:155], v[150:151], off
	s_waitcnt vmcnt(0)
	v_lshlrev_b32_e32 v156, 16, v152
	v_and_b32_e32 v157, 0xffff0000, v152
	v_lshlrev_b32_e32 v152, 16, v153
	v_and_b32_e32 v153, 0xffff0000, v153
	v_lshlrev_b32_e32 v158, 16, v154
	v_and_b32_e32 v159, 0xffff0000, v154
	v_lshlrev_b32_e32 v154, 16, v155
	v_and_b32_e32 v155, 0xffff0000, v155
	v_pk_fma_f32 v[24:25], v[24:25], v[148:149], v[152:153]
	v_pk_fma_f32 v[22:23], v[22:23], v[146:147], v[156:157]
	v_pk_fma_f32 v[28:29], v[28:29], v[144:145], v[154:155]
	v_pk_fma_f32 v[26:27], v[26:27], v[142:143], v[158:159]
	v_cvt_pk_bf16_f32 v152, v22, v23
	v_cvt_pk_bf16_f32 v153, v24, v25
	s_nop 0
	v_cvt_pk_bf16_f32 v154, v26, v27
	v_cvt_pk_bf16_f32 v155, v28, v29
	global_store_dwordx4 v[150:151], v[152:155], off
	global_load_dwordx4 v[152:155], v[150:151], off offset:256
	s_waitcnt vmcnt(0)
	v_lshlrev_b32_e32 v156, 16, v152
	v_and_b32_e32 v157, 0xffff0000, v152
	v_lshlrev_b32_e32 v152, 16, v153
	v_and_b32_e32 v153, 0xffff0000, v153
	v_lshlrev_b32_e32 v158, 16, v154
	v_and_b32_e32 v159, 0xffff0000, v154
	v_lshlrev_b32_e32 v154, 16, v155
	v_and_b32_e32 v155, 0xffff0000, v155
	v_pk_fma_f32 v[50:51], v[50:51], v[138:139], v[156:157]
	v_add_co_u32_e32 v156, vcc, s2, v150
	v_pk_fma_f32 v[52:53], v[52:53], v[140:141], v[152:153]
	v_pk_fma_f32 v[48:49], v[48:49], v[136:137], v[154:155]
	v_pk_fma_f32 v[46:47], v[46:47], v[134:135], v[158:159]
	v_cvt_pk_bf16_f32 v152, v50, v51
	v_cvt_pk_bf16_f32 v153, v52, v53
	v_addc_co_u32_e32 v157, vcc, 0, v151, vcc
	v_cvt_pk_bf16_f32 v154, v46, v47
	v_cvt_pk_bf16_f32 v155, v48, v49
	global_store_dwordx4 v[150:151], v[152:155], off offset:256
	global_load_dwordx4 v[152:155], v[156:157], off
	s_mov_b32 s2, 0x20000
	v_mul_f32_e32 v0, v23, v23
	v_fmac_f32_e32 v0, v22, v22
	s_waitcnt vmcnt(0)
	v_lshlrev_b32_e32 v158, 16, v152
	v_and_b32_e32 v159, 0xffff0000, v152
	v_lshlrev_b32_e32 v152, 16, v153
	v_and_b32_e32 v153, 0xffff0000, v153
	v_lshlrev_b32_e32 v160, 16, v154
	v_and_b32_e32 v161, 0xffff0000, v154
	v_lshlrev_b32_e32 v154, 16, v155
	v_and_b32_e32 v155, 0xffff0000, v155
	v_pk_fma_f32 v[20:21], v[20:21], v[148:149], v[152:153]
	v_pk_fma_f32 v[18:19], v[18:19], v[146:147], v[158:159]
	v_pk_fma_f32 v[12:13], v[12:13], v[144:145], v[154:155]
	v_pk_fma_f32 v[10:11], v[10:11], v[142:143], v[160:161]
	v_cvt_pk_bf16_f32 v152, v18, v19
	v_cvt_pk_bf16_f32 v153, v20, v21
	s_nop 0
	v_cvt_pk_bf16_f32 v154, v10, v11
	v_cvt_pk_bf16_f32 v155, v12, v13
	global_store_dwordx4 v[156:157], v[152:155], off
	global_load_dwordx4 v[152:155], v[156:157], off offset:256
	s_waitcnt vmcnt(0)
	v_lshlrev_b32_e32 v158, 16, v152
	v_and_b32_e32 v159, 0xffff0000, v152
	v_lshlrev_b32_e32 v152, 16, v153
	v_and_b32_e32 v153, 0xffff0000, v153
	v_lshlrev_b32_e32 v160, 16, v154
	v_and_b32_e32 v161, 0xffff0000, v154
	v_lshlrev_b32_e32 v154, 16, v155
	v_and_b32_e32 v155, 0xffff0000, v155
	v_pk_fma_f32 v[8:9], v[8:9], v[140:141], v[152:153]
	v_pk_fma_f32 v[6:7], v[6:7], v[138:139], v[158:159]
	v_pk_fma_f32 v[4:5], v[4:5], v[136:137], v[154:155]
	v_pk_fma_f32 v[2:3], v[2:3], v[134:135], v[160:161]
	v_cvt_pk_bf16_f32 v152, v6, v7
	v_cvt_pk_bf16_f32 v153, v8, v9
	s_nop 0
	v_cvt_pk_bf16_f32 v154, v2, v3
	v_cvt_pk_bf16_f32 v155, v4, v5
	global_store_dwordx4 v[156:157], v[152:155], off offset:256
	v_add_co_u32_e32 v156, vcc, s2, v150
	s_mov_b32 s2, 0x30000
	s_nop 0
	v_addc_co_u32_e32 v157, vcc, 0, v151, vcc
	global_load_dwordx4 v[152:155], v[156:157], off
	s_waitcnt vmcnt(0)
	v_lshlrev_b32_e32 v158, 16, v152
	v_and_b32_e32 v159, 0xffff0000, v152
	v_lshlrev_b32_e32 v152, 16, v153
	v_and_b32_e32 v153, 0xffff0000, v153
	v_lshlrev_b32_e32 v160, 16, v154
	v_and_b32_e32 v161, 0xffff0000, v154
	v_lshlrev_b32_e32 v154, 16, v155
	v_and_b32_e32 v155, 0xffff0000, v155
	v_pk_fma_f32 v[32:33], v[32:33], v[148:149], v[152:153]
	v_pk_fma_f32 v[30:31], v[30:31], v[146:147], v[158:159]
	v_pk_fma_f32 v[36:37], v[36:37], v[144:145], v[154:155]
	v_pk_fma_f32 v[34:35], v[34:35], v[142:143], v[160:161]
	v_cvt_pk_bf16_f32 v152, v30, v31
	v_cvt_pk_bf16_f32 v153, v32, v33
	s_nop 0
	v_cvt_pk_bf16_f32 v154, v34, v35
	v_cvt_pk_bf16_f32 v155, v36, v37
	global_store_dwordx4 v[156:157], v[152:155], off
	global_load_dwordx4 v[152:155], v[156:157], off offset:256
	s_waitcnt vmcnt(0)
	v_lshlrev_b32_e32 v158, 16, v152
	v_and_b32_e32 v159, 0xffff0000, v152
	v_lshlrev_b32_e32 v152, 16, v153
	v_and_b32_e32 v153, 0xffff0000, v153
	v_lshlrev_b32_e32 v160, 16, v154
	v_and_b32_e32 v161, 0xffff0000, v154
	v_lshlrev_b32_e32 v154, 16, v155
	v_and_b32_e32 v155, 0xffff0000, v155
	v_pk_fma_f32 v[44:45], v[44:45], v[140:141], v[152:153]
	v_pk_fma_f32 v[42:43], v[42:43], v[138:139], v[158:159]
	v_pk_fma_f32 v[40:41], v[40:41], v[136:137], v[154:155]
	v_pk_fma_f32 v[38:39], v[38:39], v[134:135], v[160:161]
	v_cvt_pk_bf16_f32 v152, v42, v43
	v_cvt_pk_bf16_f32 v153, v44, v45
	s_nop 0
	v_cvt_pk_bf16_f32 v154, v38, v39
	v_cvt_pk_bf16_f32 v155, v40, v41
	global_store_dwordx4 v[156:157], v[152:155], off offset:256
	v_add_co_u32_e32 v156, vcc, s2, v150
	s_mov_b32 s2, 0x80000
	s_nop 0
	v_addc_co_u32_e32 v157, vcc, 0, v151, vcc
	global_load_dwordx4 v[152:155], v[156:157], off
	s_waitcnt vmcnt(0)
	v_lshlrev_b32_e32 v158, 16, v152
	v_and_b32_e32 v159, 0xffff0000, v152
	v_lshlrev_b32_e32 v152, 16, v153
	v_and_b32_e32 v153, 0xffff0000, v153
	v_lshlrev_b32_e32 v160, 16, v154
	v_and_b32_e32 v161, 0xffff0000, v154
	v_lshlrev_b32_e32 v154, 16, v155
	v_and_b32_e32 v155, 0xffff0000, v155
	v_pk_fma_f32 v[56:57], v[56:57], v[148:149], v[152:153]
	v_pk_fma_f32 v[54:55], v[54:55], v[146:147], v[158:159]
	v_pk_fma_f32 v[60:61], v[60:61], v[144:145], v[154:155]
	v_pk_fma_f32 v[58:59], v[58:59], v[142:143], v[160:161]
	v_cvt_pk_bf16_f32 v152, v54, v55
	v_cvt_pk_bf16_f32 v153, v56, v57
	s_nop 0
	v_cvt_pk_bf16_f32 v154, v58, v59
	v_cvt_pk_bf16_f32 v155, v60, v61
	global_store_dwordx4 v[156:157], v[152:155], off
	global_load_dwordx4 v[152:155], v[156:157], off offset:256
	s_waitcnt vmcnt(0)
	v_lshlrev_b32_e32 v158, 16, v152
	v_and_b32_e32 v159, 0xffff0000, v152
	v_lshlrev_b32_e32 v152, 16, v153
	v_and_b32_e32 v153, 0xffff0000, v153
	v_lshlrev_b32_e32 v160, 16, v154
	v_and_b32_e32 v161, 0xffff0000, v154
	v_lshlrev_b32_e32 v154, 16, v155
	v_and_b32_e32 v155, 0xffff0000, v155
	v_pk_fma_f32 v[68:69], v[68:69], v[140:141], v[152:153]
	v_pk_fma_f32 v[66:67], v[66:67], v[138:139], v[158:159]
	v_pk_fma_f32 v[64:65], v[64:65], v[136:137], v[154:155]
	v_pk_fma_f32 v[62:63], v[62:63], v[134:135], v[160:161]
	v_cvt_pk_bf16_f32 v152, v66, v67
	v_cvt_pk_bf16_f32 v153, v68, v69
	s_nop 0
	v_cvt_pk_bf16_f32 v154, v62, v63
	v_cvt_pk_bf16_f32 v155, v64, v65
	global_store_dwordx4 v[156:157], v[152:155], off offset:256
	v_add_co_u32_e32 v156, vcc, s2, v150
	s_mov_b32 s2, 0x90000
	s_nop 0
	v_addc_co_u32_e32 v157, vcc, 0, v151, vcc
	global_load_dwordx4 v[152:155], v[156:157], off
	s_waitcnt vmcnt(0)
	v_lshlrev_b32_e32 v158, 16, v152
	v_and_b32_e32 v159, 0xffff0000, v152
	v_lshlrev_b32_e32 v152, 16, v153
	v_and_b32_e32 v153, 0xffff0000, v153
	v_lshlrev_b32_e32 v160, 16, v154
	v_and_b32_e32 v161, 0xffff0000, v154
	v_lshlrev_b32_e32 v154, 16, v155
	v_and_b32_e32 v155, 0xffff0000, v155
	v_pk_fma_f32 v[72:73], v[72:73], v[148:149], v[152:153]
	v_pk_fma_f32 v[70:71], v[70:71], v[146:147], v[158:159]
	v_pk_fma_f32 v[76:77], v[76:77], v[144:145], v[154:155]
	v_pk_fma_f32 v[74:75], v[74:75], v[142:143], v[160:161]
	v_cvt_pk_bf16_f32 v152, v70, v71
	v_cvt_pk_bf16_f32 v153, v72, v73
	s_nop 0
	v_cvt_pk_bf16_f32 v154, v74, v75
	v_cvt_pk_bf16_f32 v155, v76, v77
	global_store_dwordx4 v[156:157], v[152:155], off
	global_load_dwordx4 v[152:155], v[156:157], off offset:256
	s_waitcnt vmcnt(0)
	v_lshlrev_b32_e32 v158, 16, v152
	v_and_b32_e32 v159, 0xffff0000, v152
	v_lshlrev_b32_e32 v152, 16, v153
	v_and_b32_e32 v153, 0xffff0000, v153
	v_lshlrev_b32_e32 v160, 16, v154
	v_and_b32_e32 v161, 0xffff0000, v154
	v_lshlrev_b32_e32 v154, 16, v155
	v_and_b32_e32 v155, 0xffff0000, v155
	v_pk_fma_f32 v[84:85], v[84:85], v[140:141], v[152:153]
	v_pk_fma_f32 v[82:83], v[82:83], v[138:139], v[158:159]
	v_pk_fma_f32 v[80:81], v[80:81], v[136:137], v[154:155]
	v_pk_fma_f32 v[78:79], v[78:79], v[134:135], v[160:161]
	v_cvt_pk_bf16_f32 v152, v82, v83
	v_cvt_pk_bf16_f32 v153, v84, v85
	s_nop 0
	v_cvt_pk_bf16_f32 v154, v78, v79
	v_cvt_pk_bf16_f32 v155, v80, v81
	global_store_dwordx4 v[156:157], v[152:155], off offset:256
	v_add_co_u32_e32 v156, vcc, s2, v150
	s_mov_b32 s2, 0xa0000
	s_nop 0
	v_addc_co_u32_e32 v157, vcc, 0, v151, vcc
	global_load_dwordx4 v[152:155], v[156:157], off
	s_waitcnt vmcnt(0)
	v_lshlrev_b32_e32 v158, 16, v152
	v_and_b32_e32 v159, 0xffff0000, v152
	v_lshlrev_b32_e32 v152, 16, v153
	v_and_b32_e32 v153, 0xffff0000, v153
	v_lshlrev_b32_e32 v160, 16, v154
	v_and_b32_e32 v161, 0xffff0000, v154
	v_lshlrev_b32_e32 v154, 16, v155
	v_and_b32_e32 v155, 0xffff0000, v155
	v_pk_fma_f32 v[88:89], v[88:89], v[148:149], v[152:153]
	v_pk_fma_f32 v[86:87], v[86:87], v[146:147], v[158:159]
	v_pk_fma_f32 v[92:93], v[92:93], v[144:145], v[154:155]
	v_pk_fma_f32 v[90:91], v[90:91], v[142:143], v[160:161]
	v_cvt_pk_bf16_f32 v152, v86, v87
	v_cvt_pk_bf16_f32 v153, v88, v89
	s_nop 0
	v_cvt_pk_bf16_f32 v154, v90, v91
	v_cvt_pk_bf16_f32 v155, v92, v93
	global_store_dwordx4 v[156:157], v[152:155], off
	global_load_dwordx4 v[152:155], v[156:157], off offset:256
	s_waitcnt vmcnt(0)
	v_lshlrev_b32_e32 v158, 16, v152
	v_and_b32_e32 v159, 0xffff0000, v152
	v_lshlrev_b32_e32 v152, 16, v153
	v_and_b32_e32 v153, 0xffff0000, v153
	v_lshlrev_b32_e32 v160, 16, v154
	v_and_b32_e32 v161, 0xffff0000, v154
	v_lshlrev_b32_e32 v154, 16, v155
	v_and_b32_e32 v155, 0xffff0000, v155
	v_pk_fma_f32 v[100:101], v[100:101], v[140:141], v[152:153]
	v_pk_fma_f32 v[98:99], v[98:99], v[138:139], v[158:159]
	v_pk_fma_f32 v[96:97], v[96:97], v[136:137], v[154:155]
	v_pk_fma_f32 v[94:95], v[94:95], v[134:135], v[160:161]
	v_cvt_pk_bf16_f32 v152, v98, v99
	v_cvt_pk_bf16_f32 v153, v100, v101
	s_nop 0
	v_cvt_pk_bf16_f32 v154, v94, v95
	v_cvt_pk_bf16_f32 v155, v96, v97
	global_store_dwordx4 v[156:157], v[152:155], off offset:256
	v_add_co_u32_e32 v156, vcc, s2, v150
	s_mov_b32 s2, 0xb0000
	s_nop 0
	v_addc_co_u32_e32 v157, vcc, 0, v151, vcc
	global_load_dwordx4 v[152:155], v[156:157], off
	s_waitcnt vmcnt(0)
	v_lshlrev_b32_e32 v158, 16, v152
	v_and_b32_e32 v159, 0xffff0000, v152
	v_lshlrev_b32_e32 v152, 16, v153
	v_and_b32_e32 v153, 0xffff0000, v153
	v_lshlrev_b32_e32 v160, 16, v154
	v_and_b32_e32 v161, 0xffff0000, v154
	v_lshlrev_b32_e32 v154, 16, v155
	v_and_b32_e32 v155, 0xffff0000, v155
	v_pk_fma_f32 v[104:105], v[104:105], v[148:149], v[152:153]
	v_pk_fma_f32 v[102:103], v[102:103], v[146:147], v[158:159]
	v_pk_fma_f32 v[108:109], v[108:109], v[144:145], v[154:155]
	v_pk_fma_f32 v[106:107], v[106:107], v[142:143], v[160:161]
	v_cvt_pk_bf16_f32 v152, v102, v103
	v_cvt_pk_bf16_f32 v153, v104, v105
	s_nop 0
	v_cvt_pk_bf16_f32 v154, v106, v107
	v_cvt_pk_bf16_f32 v155, v108, v109
	global_store_dwordx4 v[156:157], v[152:155], off
	global_load_dwordx4 v[152:155], v[156:157], off offset:256
	s_waitcnt vmcnt(0)
	v_lshlrev_b32_e32 v158, 16, v152
	v_and_b32_e32 v159, 0xffff0000, v152
	v_lshlrev_b32_e32 v152, 16, v153
	v_and_b32_e32 v153, 0xffff0000, v153
	v_lshlrev_b32_e32 v160, 16, v154
	v_and_b32_e32 v161, 0xffff0000, v154
	v_lshlrev_b32_e32 v154, 16, v155
	v_and_b32_e32 v155, 0xffff0000, v155
	v_pk_fma_f32 v[116:117], v[116:117], v[140:141], v[152:153]
	v_pk_fma_f32 v[114:115], v[114:115], v[138:139], v[158:159]
	v_pk_fma_f32 v[112:113], v[112:113], v[136:137], v[154:155]
	v_pk_fma_f32 v[110:111], v[110:111], v[134:135], v[160:161]
	v_cvt_pk_bf16_f32 v152, v114, v115
	v_cvt_pk_bf16_f32 v153, v116, v117
	s_nop 0
	v_cvt_pk_bf16_f32 v154, v110, v111
	v_cvt_pk_bf16_f32 v155, v112, v113
	global_store_dwordx4 v[156:157], v[152:155], off offset:256
	s_nop 1
	v_add_co_u32_e32 v154, vcc, s2, v150
	s_nop 1
	v_addc_co_u32_e32 v155, vcc, 0, v151, vcc
	global_load_dwordx4 v[150:153], v[154:155], off
	s_waitcnt vmcnt(0)
	v_lshlrev_b32_e32 v156, 16, v150
	v_and_b32_e32 v157, 0xffff0000, v150
	v_lshlrev_b32_e32 v150, 16, v151
	v_and_b32_e32 v151, 0xffff0000, v151
	v_lshlrev_b32_e32 v158, 16, v152
	v_and_b32_e32 v159, 0xffff0000, v152
	v_lshlrev_b32_e32 v152, 16, v153
	v_and_b32_e32 v153, 0xffff0000, v153
	v_pk_fma_f32 v[120:121], v[120:121], v[148:149], v[150:151]
	v_pk_fma_f32 v[118:119], v[118:119], v[146:147], v[156:157]
	v_pk_fma_f32 v[124:125], v[124:125], v[144:145], v[152:153]
	v_pk_fma_f32 v[122:123], v[122:123], v[142:143], v[158:159]
	v_cvt_pk_bf16_f32 v142, v118, v119
	v_cvt_pk_bf16_f32 v143, v120, v121
	s_nop 0
	v_cvt_pk_bf16_f32 v144, v122, v123
	v_cvt_pk_bf16_f32 v145, v124, v125
	global_store_dwordx4 v[154:155], v[142:145], off
	global_load_dwordx4 v[142:145], v[154:155], off offset:256
	s_waitcnt vmcnt(0)
	v_lshlrev_b32_e32 v146, 16, v142
	v_and_b32_e32 v147, 0xffff0000, v142
	v_lshlrev_b32_e32 v148, 16, v144
	v_and_b32_e32 v149, 0xffff0000, v144
	v_lshlrev_b32_e32 v142, 16, v143
	v_and_b32_e32 v143, 0xffff0000, v143
	v_lshlrev_b32_e32 v144, 16, v145
	v_and_b32_e32 v145, 0xffff0000, v145
	v_pk_fma_f32 v[130:131], v[130:131], v[138:139], v[146:147]
	v_pk_fma_f32 v[126:127], v[126:127], v[134:135], v[148:149]
	v_cvt_pk_bf16_f32 v134, v130, v131
	v_pk_fma_f32 v[132:133], v[132:133], v[140:141], v[142:143]
	v_pk_fma_f32 v[128:129], v[128:129], v[136:137], v[144:145]
	v_cvt_pk_bf16_f32 v135, v132, v133
	v_cvt_pk_bf16_f32 v136, v126, v127
	s_nop 0
	v_cvt_pk_bf16_f32 v137, v128, v129
	global_store_dwordx4 v[154:155], v[134:137], off offset:256
	s_nop 1
	v_mul_f32_e32 v134, v25, v25
	v_fmac_f32_e32 v134, v24, v24
	v_add_f32_e32 v0, v0, v134
	v_mul_f32_e32 v134, v27, v27
	v_mul_f32_e32 v135, v29, v29
	v_fmac_f32_e32 v134, v26, v26
	v_fmac_f32_e32 v135, v28, v28
	v_add_f32_e32 v134, v134, v135
	v_add_f32_e32 v0, v0, v134
	v_mul_f32_e32 v134, v51, v51
	v_mul_f32_e32 v135, v53, v53
	v_fmac_f32_e32 v134, v50, v50
	v_fmac_f32_e32 v135, v52, v52
	v_add_f32_e32 v134, v134, v135
	v_add_f32_e32 v0, v134, v0
	v_mul_f32_e32 v134, v47, v47
	v_mul_f32_e32 v135, v49, v49
	v_fmac_f32_e32 v134, v46, v46
	v_fmac_f32_e32 v135, v48, v48
	v_add_f32_e32 v134, v134, v135
	v_add_f32_e32 v0, v134, v0
	ds_bpermute_b32 v134, v246, v0
	s_waitcnt lgkmcnt(0)
	v_add_f32_e32 v0, v0, v134
	ds_bpermute_b32 v134, v247, v0
	s_mov_b64 s[10:11], exec
	s_and_b64 s[66:67], s[10:11], s[12:13]
	v_mov_b32_e32 v237, v242
	s_mov_b64 exec, s[66:67]
	s_cbranch_execz .LBB0_1647
	s_waitcnt lgkmcnt(0)
	v_add_f32_e32 v0, v0, v134
	ds_write_b32 v252, v0
